# one static priority raise at entry for waves 4-7 (no per-segment toggles)
# baseline (speedup 1.0000x reference)
; #define LAS __attribute__((address_space(3)))
; template <class T> __device__ __forceinline__ T* as_global(T* p) { return (T*)(GAS T*)p; }
; __device__ __forceinline__ unsigned xb_xcc_id() { return (unsigned)__builtin_amdgcn_s_getreg((3 << 11) | 20) & 0xFu; }
; __global__ void __launch_bounds__(NWAVES * 64, 2) fwd_kernel(Args a) {
;     extern __shared__ __attribute__((aligned(16))) unsigned char lds_raw[];
;     LAS unsigned char* lds = (LAS unsigned char*)lds_raw;
;     const int G = gridDim.x, cu = blockIdx.x;
;     const int lo = a.ph_lo, hi = a.ph_hi;
;     const bool spread = (G == 256) && MK_ONE;
;     ...
;     cg::grid_group grid = cg::this_grid();
;     { volatile LAS unsigned* misc = (volatile LAS unsigned*)(lds + MISC_OFF); if (threadIdx.x < 32) misc[threadIdx.x] = 0u; __syncthreads(); }
;     XcdBarrier bar; bar.bar = (unsigned*)(as_global(a.ws) + WS_BAR); bar.x = xb_xcc_id(); bar.st = (volatile LAS unsigned*)(lds + MISC_OFF) + 8;
;     ...
;     if (!(SKIP & 32) && IN(0)) {
_Z10fwd_kernel4Args:
	s_load_dwordx4 s[68:71], s[0:1], 0xa8
	s_add_u32 s10, s0, 0xb0
	v_and_b32_e32 v210, 0x3ff, v0
	s_addc_u32 s11, s1, 0
	v_cmp_gt_u32_e32 vcc, 32, v210
	v_lshl_add_u32 v135, v210, 2, 0
	v_lshrrev_b32_e32 v1, 6, v210
	v_readfirstlane_b32 s4, v1
	s_nop 3
	s_cmp_lt_u32 s4, 4
	s_cbranch_scc1 .Lprio_keep
	s_setprio 1
.Lprio_keep:
	s_and_saveexec_b64 s[4:5], vcc
	v_add_u32_e32 v1, 0x23040, v135
	v_mov_b32_e32 v2, 0
	ds_write_b32 v1, v2
	s_or_b64 exec, exec, s[4:5]
	s_load_dwordx2 s[94:95], s[0:1], 0xa0
	s_waitcnt lgkmcnt(0)
	s_cmpk_eq_i32 s70, 0x100
	s_cselect_b64 s[4:5], -1, 0
	s_cmpk_lg_i32 s70, 0x100
	v_writelane_b32 v252, s4, 0
	s_barrier
	s_nop 0
	v_writelane_b32 v252, s5, 1
	s_cselect_b64 s[4:5], -1, 0
	s_add_u32 s24, s94, 0x15600000
	s_addc_u32 s25, s95, 0
	s_cmp_lt_i32 s68, 1
	s_cselect_b64 s[6:7], -1, 0
	s_cmp_gt_i32 s69, 0
	s_cselect_b64 s[8:9], -1, 0
	s_and_b64 s[6:7], s[6:7], s[8:9]
	s_getreg_b32 s3, hwreg(HW_REG_XCC_ID, 0, 4)
	s_and_b64 vcc, exec, s[6:7]
	v_and_b32_e32 v1, 63, v210
	s_cbranch_vccnz .LBB0_4
	s_lshl_b32 s36, s2, 3
	v_and_b32_e32 v212, 63, v210
	s_and_b32 s33, s3, 15
	s_cbranch_execz .LBB0_5
	s_branch .LBB0_190
